# mixer phase: static priority raise for waves 0-3 for the whole phase (one prioritized wave per SIMD)
# speedup vs baseline: 1.0127x; 1.0057x over previous
; #define LAS __attribute__((address_space(3)))
; __device__ __forceinline__ void mixer_chunk(KP p, LAS unsigned char* lds, int l, int chunk) {
;     int tid = threadIdx.x; asm volatile("" : "+v"(tid));
;     const int lane = tid & 63, w = __builtin_amdgcn_readfirstlane(tid >> 6), fr = lane & 15, fq = lane >> 4;
;     unsigned char* ws = p->ws;
;     const bf16_t* zb = (const bf16_t*)(ws + OFF_ZB);
;     bf16_t* mixed = (bf16_t*)(ws + OFF_MIX);
;     const int c0 = chunk * 128, bidx = chunk >> 5, s0 = (chunk & 31) * 128;
;     LAS bf16_t* Y = (LAS bf16_t*)lds; LAS bf16_t* CO = (LAS bf16_t*)(lds + R2_OFF); LAS bf16_t* VT = (LAS bf16_t*)lds;
;     LAS bf16_t* CQ = (LAS bf16_t*)lds; LAS bf16_t* CK = (LAS bf16_t*)(lds + CK_OFF); LAS float* RSQ = (LAS float*)(lds + RS_OFF); LAS float* RSK = RSQ + 128;
;     LAS bf16_t* ZP = (LAS bf16_t*)lds; LAS bf16_t* YP = (LAS bf16_t*)(lds + R2_OFF);
;     LAS float* part0 = (LAS float*)(lds + R3_OFF); LAS float* part1 = part0 + 1024;
;     bf16_t* mrow = mixed + (size_t)(c0 + fr) * DM + 4 * fq;
; __global__ void __launch_bounds__(512) fwd_kernel(Params p_arg) {
;     ...
;             for (int ch = blockIdx.x; ch < M_TOK / 128; ch += gridDim.x) mixer_chunk(p, lds, l, ch);
.LBB0_278:
	s_andn2_b64 vcc, exec, s[4:5]
	s_cbranch_vccnz .LBB0_435
	s_and_b64 vcc, exec, s[40:41]
	s_cbranch_vccnz .LBB0_435
	s_lshl_b32 s6, s22, 8
	s_ashr_i32 s7, s6, 31
	s_lshl_b64 s[4:5], s[22:23], 17
	s_lshl_b64 s[24:25], s[22:23], 15
	s_lshl_b32 s10, s22, 9
	s_waitcnt lgkmcnt(0)
	v_readfirstlane_b32 s100, v167
	s_nop 3
	s_cmp_ge_u32 s100, 0x100
	s_cbranch_scc1 .Lmx_prio_done
	s_setprio 1

; #define LAS __attribute__((address_space(3)))
; __device__ __forceinline__ void mixer_chunk(KP p, LAS unsigned char* lds, int l, int chunk) {
;     int tid = threadIdx.x; asm volatile("" : "+v"(tid));
;     const int lane = tid & 63, w = __builtin_amdgcn_readfirstlane(tid >> 6), fr = lane & 15, fq = lane >> 4;
;     unsigned char* ws = p->ws;
;     const bf16_t* zb = (const bf16_t*)(ws + OFF_ZB);
;     bf16_t* mixed = (bf16_t*)(ws + OFF_MIX);
;     const int c0 = chunk * 128, bidx = chunk >> 5, s0 = (chunk & 31) * 128;
;     LAS bf16_t* Y = (LAS bf16_t*)lds; LAS bf16_t* CO = (LAS bf16_t*)(lds + R2_OFF); LAS bf16_t* VT = (LAS bf16_t*)lds;
;     LAS bf16_t* CQ = (LAS bf16_t*)lds; LAS bf16_t* CK = (LAS bf16_t*)(lds + CK_OFF); LAS float* RSQ = (LAS float*)(lds + RS_OFF); LAS float* RSK = RSQ + 128;
;     LAS bf16_t* ZP = (LAS bf16_t*)lds; LAS bf16_t* YP = (LAS bf16_t*)(lds + R2_OFF);
;     LAS float* part0 = (LAS float*)(lds + R3_OFF); LAS float* part1 = part0 + 1024;
;     bf16_t* mrow = mixed + (size_t)(c0 + fr) * DM + 4 * fq;
.Lpad_mp:
	s_add_u32 s44, s94, 0xa0b0000
	s_addc_u32 s45, s95, 0
	v_writelane_b32 v252, s10, 4
	s_add_u32 s10, s94, 0x110b0000
	s_addc_u32 s11, s95, 0
	s_add_u32 s18, s94, s4
	s_addc_u32 s23, s95, s5
	s_add_u32 s4, s18, 0x5600000
	s_addc_u32 s5, s23, 0
	s_add_u32 s92, s94, 0x9cb0000
	v_writelane_b32 v252, s10, 6
	s_addc_u32 s93, s95, 0
	s_add_u32 s12, s94, 0x168b0000
	v_writelane_b32 v252, s11, 7
	s_mul_i32 s9, s22, 0x24000
	v_writelane_b32 v252, s4, 8
	s_addc_u32 s13, s95, 0
	s_mul_hi_i32 s8, s22, 0x24000
	v_writelane_b32 v252, s5, 9
	s_add_u32 s4, s94, s9
	s_addc_u32 s5, s95, s8
	s_add_u32 s10, s4, 0x5680000
	s_addc_u32 s11, s5, 0
	s_add_u32 s4, s94, 0x150b0000
	v_writelane_b32 v252, s4, 10
	s_addc_u32 s4, s95, 0
	s_add_u32 s84, s18, 0x5710000
	s_addc_u32 s85, s23, 0
	s_add_u32 s8, s94, 0x180b0000
	s_addc_u32 s9, s95, 0
	v_writelane_b32 v252, s4, 11
	s_add_u32 s4, s94, s24
	s_addc_u32 s5, s95, s25
	s_add_u32 s4, s4, 0x5790000
	s_addc_u32 s5, s5, 0
	s_add_u32 s48, s18, 0x57b0000
	s_mov_b32 s83, s88
	s_addc_u32 s49, s23, 0
	s_lshl_b64 s[36:37], s[6:7], 2
	s_mov_b32 s23, s2
	s_branch .LBB0_282

; __device__ __forceinline__ float bf_lo(unsigned w) { return __uint_as_float(w << 16); }
; __device__ __forceinline__ float bf_hi(unsigned w) { return __uint_as_float(w & 0xffff0000u); }
; __device__ __forceinline__ void mixer_chunk(KP p, LAS unsigned char* lds, int l, int chunk) {
;     ...
;                     const int mt = 2 * mp + q; const u32x2 u2 = uu[2 * mt + n]; const float bs_ = bias[mt];
;                     a[0] = bf_lo(u2.x) * (a[0] + bs_); a[1] = bf_hi(u2.x) * (a[1] + bs_); a[2] = bf_lo(u2.y) * (a[2] + bs_); a[3] = bf_hi(u2.y) * (a[3] + bs_);
;                     acc[mt][n] = a; }
;         }
;         part_sumsq<2>(acc, part0, w, fr, fq);
.LBB0_432:
	s_or_b64 exec, exec, s[6:7]
	v_lshlrev_b32_e32 v6, 16, v100
	s_waitcnt lgkmcnt(0)
	v_add_f32_e32 v7, v128, v18
	v_mul_f32_e32 v6, v7, v6
	v_and_b32_e32 v7, 0xffff0000, v100
	v_add_f32_e32 v8, v128, v19
	v_mul_f32_e32 v7, v8, v7
	v_lshlrev_b32_e32 v8, 16, v101
	v_add_f32_e32 v9, v128, v20
	v_mul_f32_e32 v8, v9, v8
	v_and_b32_e32 v9, 0xffff0000, v101
	v_add_f32_e32 v18, v128, v21
	v_mul_f32_e32 v9, v18, v9
	v_lshlrev_b32_e32 v18, 16, v98
	v_add_f32_e32 v2, v128, v2
	v_mul_f32_e32 v2, v2, v18
	v_and_b32_e32 v18, 0xffff0000, v98
	v_add_f32_e32 v3, v128, v3
	v_mul_f32_e32 v3, v3, v18
	v_lshlrev_b32_e32 v18, 16, v99
	v_add_f32_e32 v4, v128, v4
	v_mul_f32_e32 v4, v4, v18
	v_and_b32_e32 v18, 0xffff0000, v99
	v_add_f32_e32 v5, v128, v5
	v_mul_f32_e32 v5, v5, v18
	v_mul_f32_e32 v18, v7, v7
	v_mul_f32_e32 v19, v9, v9
	v_fmac_f32_e32 v18, v6, v6
	v_fmac_f32_e32 v19, v8, v8
	v_add_f32_e32 v18, v18, v19
	v_mul_f32_e32 v19, v3, v3
	v_mul_f32_e32 v20, v5, v5
	v_fmac_f32_e32 v19, v2, v2
	v_fmac_f32_e32 v20, v4, v4
	v_add_f32_e32 v19, v19, v20
	v_add_f32_e32 v18, v18, v19
	ds_bpermute_b32 v19, v207, v18
	s_waitcnt lgkmcnt(0)
	v_add_f32_e32 v18, v18, v19
	ds_bpermute_b32 v19, v208, v18
	s_and_saveexec_b64 s[6:7], s[40:41]
	s_cbranch_execz .LBB0_281
	s_waitcnt lgkmcnt(0)
	v_add_f32_e32 v18, v18, v19
	ds_write_b32 v216, v18 offset:3584
	s_branch .LBB0_281
.LBB0_434:
	s_setprio 0
	s_branch .Lpad_mp2
	s_nop 0
	s_nop 0
	s_nop 0
	s_nop 0
	s_nop 0
	s_nop 0
	s_nop 0
	s_nop 0
	s_nop 0
	s_nop 0
	s_nop 0
	s_nop 0
	s_nop 0
	s_nop 0
.Lpad_mp2:
	v_readlane_b32 s84, v253, 0
	s_mov_b32 s88, s83
	v_readlane_b32 s85, v253, 1
